# v54: rope_item loop 4 (E2 copy on workgroups >= 128) issues its eight ds_read_u16 first, one LDS round trip per iteration instead of four
# speedup vs baseline: 1.0077x; 1.0077x over previous
.LBB0_1489:
	ds_read_u16 v5, v4
	ds_read_u16 v6, v4 offset:144
	ds_read_u16 v12, v4 offset:288
	ds_read_u16 v7, v4 offset:432
	ds_read_u16 v13, v4 offset:576
	ds_read_u16 v8, v4 offset:720
	ds_read_u16 v14, v4 offset:864
	ds_read_u16 v9, v4 offset:1008
	s_and_b32 s1, s3, 1
	s_cmp_lt_u32 s3, 2
	s_cselect_b32 s5, s87, 0x13300000
	s_add_u32 s5, s64, s5
	s_waitcnt lgkmcnt(0)
	v_lshl_or_b32 v6, v6, 16, v5
	s_addc_u32 s14, s65, 0
	s_or_b32 s54, s1, s4
	s_lshl_b64 s[6:7], s[54:55], 18
	s_add_u32 s6, s5, s6
	s_waitcnt lgkmcnt(0)
	v_lshl_or_b32 v7, v7, 16, v12
	s_addc_u32 s7, s14, s7
	v_lshl_add_u64 v[10:11], s[6:7], 0, v[2:3]
	s_mov_b32 s1, s55
	v_lshl_add_u64 v[10:11], v[10:11], 0, s[0:1]
	s_waitcnt lgkmcnt(0)
	v_lshl_or_b32 v8, v8, 16, v13
	s_add_i32 s3, s3, 1
	v_lshl_add_u64 v[10:11], v[10:11], 0, v[0:1]
	v_add_u32_e32 v4, 0x2400, v4
	s_cmp_lg_u32 s3, 4
	s_waitcnt lgkmcnt(0)
	v_lshl_or_b32 v9, v9, 16, v14
	global_store_dwordx4 v[10:11], v[6:9], off
	s_cbranch_scc1 .LBB0_1489
	s_lshl_b32 s0, s26, 9
	s_and_b32 s6, s2, 0xffffff80
	s_and_b32 s0, s0, 0x200
	v_readlane_b32 s1, v255, 1
	s_addk_i32 s6, 0xe000
	s_add_i32 s7, s1, s0
	s_add_u32 s14, s64, s0
	s_addc_u32 s15, s65, 0
	s_mov_b64 s[0:1], 0
	s_barrier
	s_branch .LBB0_1492
